# scan LDS images: row pad 16->32 bytes in ret and hg2 scans (conflict-free ds_read_b128 fragment reads)
# speedup vs baseline: 1.0039x; 1.0003x over previous
;     __host__ __device__ bool next(int i, Unit& u) const { return StaticOrder::next(i >> 1, u); }
;     __device__ __forceinline__ bool next(int i, Unit& u) const { const int s = i * G + c; if (s >= 128) return false; const int t = s >> 2; u.pm = pm0 + (t & 3); u.pn = t >> 2; u.k0 = (s & 3) * ksub; return true; }
;     __host__ __device__ bool next(int i, Unit& u) const {
;         const long L = (long)i * G + c; if (!(PG8_ROUND_MAJOR && G % NXCD == 0) && L >= nwg) return false; if ((long)i * G >= nwg) return false;
;         int wgid = (int)L;
;         if (PG8_ROUND_MAJOR && G % NXCD == 0) { const int per = G / NXCD; wgid = ((i * NXCD) + (c % NXCD)) * per + (c / NXCD); if (wgid >= nwg) return false; }
;         else { const int q = nwg / NXCD, r = nwg % NXCD, xcd = wgid % NXCD, off = wgid / NXCD; wgid = (xcd < r ? xcd * (q + 1) : r * (q + 1) + (xcd - r) * q) + off; }
;         const int nig = wgm * nN, gid = wgid / nig, fm = gid * wgm, gsz = (nM - fm) < wgm ? (nM - fm) : wgm;
;         u.pm = fm + ((wgid % nig) % gsz); u.pn = (wgid % nig) / gsz; u.k0 = 0; return true;
; __global__ void __launch_bounds__(NWAVES * 64, 2) fwd_kernel(Args args_in) {
;     ...
;         const bool last = (layer == DEPTH - 1), hg = (layer & 1) != 0;
;         const int j = layer >> 1;
;         const int Mr = last ? ML : M;
;     ...
;         const int tc_slot = ((int)blockIdx.x & 7) * 32 + ((int)blockIdx.x >> 3);
;         const int tc_rem1 = (hg ? (M / 256) * 40 : (M / 256) * 32) % 256, tc_idle1 = 256 - tc_rem1;
;         const float* modl = MOD + (size_t)layer * 5 * MOD_LD;
;         unsigned char* wb = ws + WS_W + (size_t)layer * W_LAYER;
.LBB0_201:
	s_cmpk_eq_i32 s3, 0x100
	s_cselect_b64 s[0:1], -1, 0
	v_writelane_b32 v254, s0, 20
	s_cmpk_lg_i32 s3, 0x100
	s_mov_b32 s85, 0
	v_writelane_b32 v254, s1, 21
	s_cselect_b64 s[0:1], -1, 0
	v_writelane_b32 v254, s0, 22
	s_ashr_i32 s97, s2, 31
	s_lshl_b32 s42, s3, 3
	v_writelane_b32 v254, s1, 23
	s_lshl_b32 s0, s2, 5
	s_and_b32 s0, s0, 0xe0
	s_ashr_i32 s1, s2, 3
	s_add_i32 s8, s0, s1
	s_lshr_b32 s0, s97, 29
	s_add_i32 s0, s2, s0
	s_ashr_i32 s10, s0, 3
	s_and_b32 s0, s0, -8
	s_sub_i32 s11, s2, s0
	s_ashr_i32 s0, s3, 3
	v_readlane_b32 s1, v254, 4
	v_writelane_b32 v254, s0, 24
	s_mul_i32 s0, s0, s11
	s_lshl_b32 s91, s1, 3
	s_add_i32 s14, s0, s10
	s_ashr_i32 s65, s3, 31
	s_cmpk_lt_i32 s1, 0x100
	s_cselect_b64 s[0:1], -1, 0
	v_writelane_b32 v254, s0, 25
	s_cmpk_lt_i32 s2, 0x200
	s_mov_b32 s52, 0xf7800000
	v_writelane_b32 v254, s1, 26
	s_cselect_b64 s[0:1], -1, 0
	s_lshl_b32 s6, s11, 6
	s_cmpk_lt_i32 s14, 0x200
	s_cselect_b64 s[4:5], -1, 0
	s_cmpk_lt_i32 s2, 0x80
	s_cselect_b64 s[12:13], -1, 0
	v_writelane_b32 v254, s12, 27
	s_bfe_u32 s7, s2, 0x20002
	s_or_b32 s9, s7, 64
	v_writelane_b32 v254, s13, 28
	s_lshl_b32 s7, s2, 9
	v_writelane_b32 v254, s9, 29
	s_lshl_b32 s9, s9, 20
	s_and_b32 s7, s7, 0x600
	v_writelane_b32 v254, s9, 30
	s_ashr_i32 s16, s2, 4
	v_writelane_b32 v254, s7, 31
	s_lshl_b32 s7, s7, 1
	v_writelane_b32 v254, s7, 32
	s_mov_b32 s12, s16
	s_ashr_i32 s17, s16, 31
	v_writelane_b32 v254, s12, 33
	v_cndmask_b32_e64 v1, 0, 1, s[0:1]
	v_cndmask_b32_e64 v0, 0, 1, s[4:5]
	v_writelane_b32 v254, s13, 34
	s_lshl_b64 s[12:13], s[16:17], 20
	v_writelane_b32 v254, s12, 35
	s_cmpk_gt_i32 s2, 0x7f
	v_cndmask_b32_e64 v0, v1, v0, s[38:39]
	v_writelane_b32 v254, s13, 36
	s_cselect_b64 s[12:13], -1, 0
	s_lshl_b32 s7, s2, 3
	v_writelane_b32 v254, s12, 37
	s_add_i32 s9, s7, 0xfffffc00
	s_cmpk_gt_i32 s8, 0xaf
	v_writelane_b32 v254, s13, 38
	v_writelane_b32 v254, s9, 39
	s_cselect_b64 s[12:13], -1, 0
	v_writelane_b32 v254, s12, 40
	s_addk_i32 s7, 0x2a00
	v_and_b32_e32 v0, 1, v0
	v_writelane_b32 v254, s13, 41
	v_writelane_b32 v254, s8, 42
	s_lshl_b32 s8, s8, 3
	s_addk_i32 s8, 0xa80
	v_writelane_b32 v254, s8, 43
	s_and_b32 s8, s2, 3
	v_writelane_b32 v254, s7, 44
	s_mul_i32 s9, s8, 0x580
	v_writelane_b32 v254, s9, 45
	s_mulk_i32 s8, 0xb00
	s_cmp_lt_i32 s11, 0
	v_writelane_b32 v254, s8, 46
	s_movk_i32 s8, 0x155
	s_movk_i32 s9, 0x111
	s_mul_i32 s7, s11, 0x41
	s_cselect_b32 s8, s8, 0x154
	s_cselect_b32 s9, s9, 0x110
	s_mul_i32 s8, s11, s8
	s_mul_i32 s9, s11, s9
	s_cselect_b32 s6, s7, s6
	v_writelane_b32 v254, s10, 47
	s_add_i32 s8, s8, s10
	s_add_i32 s9, s9, s10
	s_add_i32 s10, s6, s10
	v_writelane_b32 v254, s11, 48
	s_lshr_b32 s6, s11, 31
	v_writelane_b32 v254, s6, 49
	s_and_b64 s[6:7], s[38:39], exec
	s_cselect_b32 s11, s14, s2
	s_cmpk_lt_i32 s11, 0xaa0
	s_cselect_b64 s[6:7], -1, 0
	v_writelane_b32 v254, s6, 50
	s_waitcnt lgkmcnt(0)
;     __host__ __device__ bool next(int i, Unit& u) const { return StaticOrder::next(i >> 1, u); }
;     __device__ __forceinline__ bool next(int i, Unit& u) const { const int s = i * G + c; if (s >= 128) return false; const int t = s >> 2; u.pm = pm0 + (t & 3); u.pn = t >> 2; u.k0 = (s & 3) * ksub; return true; }
;     __host__ __device__ bool next(int i, Unit& u) const {
;         const long L = (long)i * G + c; if (!(PG8_ROUND_MAJOR && G % NXCD == 0) && L >= nwg) return false; if ((long)i * G >= nwg) return false;
;         int wgid = (int)L;
;         if (PG8_ROUND_MAJOR && G % NXCD == 0) { const int per = G / NXCD; wgid = ((i * NXCD) + (c % NXCD)) * per + (c / NXCD); if (wgid >= nwg) return false; }
;         else { const int q = nwg / NXCD, r = nwg % NXCD, xcd = wgid % NXCD, off = wgid / NXCD; wgid = (xcd < r ? xcd * (q + 1) : r * (q + 1) + (xcd - r) * q) + off; }
;         const int nig = wgm * nN, gid = wgid / nig, fm = gid * wgm, gsz = (nM - fm) < wgm ? (nM - fm) : wgm;
;         u.pm = fm + ((wgid % nig) % gsz); u.pn = (wgid % nig) / gsz; u.k0 = 0; return true;
; __device__ __forceinline__ void mixer_hg2(const Args& a, Frame& F, bool ctx_out) {
;     ...
;     constexpr int HD = 128, NH = 16, NEB = 2, C = 64, NCTX = CTXL / C, NCH = (CTXL + SEQ) / C, KS = HD / 32;
;     constexpr int QS = HD * 2 + 16, IMG = 64 * QS, PS = MX_PS;
;     constexpr int O_VT = 3 * IMG, O_P = O_VT + 64 * PS, O_ST = O_P + 64 * PS, O_END = O_ST + IMG;
	s_mov_b32 s69, 0x3c000
	v_mov_b32_e32 v252, 0x358637bd
	v_writelane_b32 v254, s7, 51
	s_and_b64 s[6:7], s[38:39], exec
	s_cselect_b32 s6, s14, s8
	s_mul_hi_i32 s7, s6, 0x66666667
	s_lshr_b32 s8, s7, 31
	s_ashr_i32 s7, s7, 6
	s_add_i32 s7, s7, s8
	s_lshl_b32 s8, s7, 2
	s_sub_i32 s12, 0x44, s8
	s_mulk_i32 s7, 0xa0
	s_min_i32 s12, s12, 4
	s_sub_i32 s13, s6, s7
	s_cmpk_lt_i32 s11, 0x880
	s_cselect_b64 s[6:7], -1, 0
	v_writelane_b32 v254, s6, 52
	s_mov_b32 s55, 0xf800000
	v_mov_b32_e32 v253, 0x260
	v_writelane_b32 v254, s7, 53
	s_and_b64 s[6:7], s[38:39], exec
	s_cselect_b32 s6, s14, s9
	s_ashr_i32 s7, s6, 31
	s_lshr_b32 s7, s7, 25
	s_add_i32 s7, s6, s7
	s_ashr_i32 s9, s7, 7
	s_lshl_b32 s9, s9, 2
	s_sub_i32 s11, 0x44, s9
	s_and_b32 s7, s7, 0xffffff80
	s_min_i32 s11, s11, 4
	s_sub_i32 s6, s6, s7
	s_and_b64 s[0:1], s[38:39], exec
	s_cselect_b32 s0, s14, s10
	s_abs_i32 s5, s12
	v_cvt_f32_u32_e32 v1, s5
	v_writelane_b32 v254, s14, 54
	s_sub_i32 s14, 0, s5
	s_ashr_i32 s1, s0, 31
	v_rcp_iflag_f32_e32 v1, v1
	s_lshr_b32 s1, s1, 27
	s_add_i32 s1, s0, s1
	s_abs_i32 s10, s13
	v_mul_f32_e32 v1, 0x4f7ffffe, v1
	v_cvt_u32_f32_e32 v1, v1
	s_ashr_i32 s4, s1, 5
	s_lshl_b32 s4, s4, 2
	s_andn2_b32 s1, s1, 31
	v_readfirstlane_b32 s15, v1
	s_mul_i32 s14, s14, s15
	s_mul_hi_u32 s14, s15, s14
	s_add_i32 s15, s15, s14
	s_mul_hi_u32 s14, s10, s15
	s_mul_i32 s15, s14, s5
	s_sub_i32 s7, 64, s4
	s_sub_i32 s0, s0, s1
	s_xor_b32 s1, s13, s12
	s_sub_i32 s10, s10, s15
	s_min_i32 s7, s7, 4
	s_ashr_i32 s1, s1, 31
	s_add_i32 s15, s14, 1
	s_sub_i32 s16, s10, s5
	s_cmp_ge_u32 s10, s5
	s_cselect_b32 s14, s15, s14
	s_cselect_b32 s10, s16, s10
	s_add_i32 s15, s14, 1
	s_cmp_ge_u32 s10, s5
	s_cselect_b32 s5, s15, s14
	s_abs_i32 s10, s11
	v_cvt_f32_u32_e32 v1, s10
	s_xor_b32 s5, s5, s1
	s_sub_i32 s1, s5, s1
	v_writelane_b32 v254, s1, 55
	v_rcp_iflag_f32_e32 v1, v1
	s_mul_i32 s1, s1, s12
	s_sub_i32 s1, s13, s1
	s_add_i32 s1, s8, s1
	v_mul_f32_e32 v1, 0x4f7ffffe, v1
	v_cvt_u32_f32_e32 v1, v1
	s_sub_i32 s8, 0, s10
	s_abs_i32 s5, s6
	v_writelane_b32 v254, s1, 56
	v_readfirstlane_b32 s12, v1
	s_mul_i32 s8, s8, s12
	s_mul_hi_u32 s8, s12, s8
	s_add_i32 s12, s12, s8
	s_mul_hi_u32 s8, s5, s12
	s_mul_i32 s12, s8, s10
	s_xor_b32 s1, s6, s11
	s_sub_i32 s5, s5, s12
	s_ashr_i32 s1, s1, 31
	s_add_i32 s12, s8, 1
	s_sub_i32 s13, s5, s10
	s_cmp_ge_u32 s5, s10
	s_cselect_b32 s8, s12, s8
	s_cselect_b32 s5, s13, s5
	s_add_i32 s12, s8, 1
	s_cmp_ge_u32 s5, s10
	s_cselect_b32 s5, s12, s8
	s_abs_i32 s8, s7
	v_cvt_f32_u32_e32 v1, s8
	s_xor_b32 s5, s5, s1
	s_sub_i32 s1, s5, s1
	v_writelane_b32 v254, s1, 57
	v_rcp_iflag_f32_e32 v1, v1
	s_mul_i32 s1, s1, s11
	s_sub_i32 s1, s6, s1
	s_add_i32 s1, s9, s1
	v_mul_f32_e32 v1, 0x4f7ffffe, v1
	v_cvt_u32_f32_e32 v1, v1
	s_sub_i32 s6, 0, s8
	s_abs_i32 s5, s0
	v_writelane_b32 v254, s1, 58
	v_readfirstlane_b32 s9, v1
	s_mul_i32 s6, s6, s9
	s_mul_hi_u32 s6, s9, s6
	s_add_i32 s9, s9, s6
	s_mul_hi_u32 s6, s5, s9
	s_mul_i32 s9, s6, s8
	s_xor_b32 s1, s0, s7
	s_sub_i32 s5, s5, s9
	s_ashr_i32 s1, s1, 31
	s_add_i32 s9, s6, 1
	s_sub_i32 s10, s5, s8
	s_cmp_ge_u32 s5, s8
	s_cselect_b32 s6, s9, s6
	s_cselect_b32 s5, s10, s5
	s_add_i32 s9, s6, 1
	s_cmp_ge_u32 s5, s8
	s_cselect_b32 s5, s9, s6
	s_xor_b32 s5, s5, s1
	s_sub_i32 s6, s5, s1
	s_mul_i32 s1, s6, s7
	s_sub_i32 s0, s0, s1
	s_add_i32 s4, s4, s0
	s_ashr_i32 s0, s91, 31
	v_writelane_b32 v254, s0, 59
	s_add_i32 s0, 0, 0x20160
	v_writelane_b32 v254, s0, 60
	s_add_i32 s0, 0, 0x20164
	v_writelane_b32 v254, s0, 61
	s_add_i32 s0, 0, 0x12800
	v_writelane_b32 v254, s0, 62
	s_add_i32 s0, 0, 0x13800
	v_writelane_b32 v254, s0, 63
	s_add_i32 s0, 0, 0x16000
	v_writelane_b32 v255, s0, 0
	s_add_i32 s0, 0, 0x11000
	v_writelane_b32 v255, s0, 1
	v_cmp_eq_u32_e64 s[0:1], 1, v0
	s_ashr_i32 s5, s4, 31
	s_ashr_i32 s7, s6, 31
	v_writelane_b32 v255, s0, 2
	s_ashr_i32 s43, s42, 31
	v_mov_b32_e32 v1, 0
	v_writelane_b32 v255, s1, 3
	s_mov_b32 s0, s4
	v_writelane_b32 v255, s0, 4
	s_movk_i32 s94, 0x7ff
	v_mov_b32_e32 v182, 0x42a00000
	v_writelane_b32 v255, s1, 5
	s_lshl_b64 s[0:1], s[4:5], 20
	v_writelane_b32 v255, s0, 6
	v_mov_b32_e32 v183, 0x7f800000
	s_mov_b32 s95, 0xc2a00000
	v_writelane_b32 v255, s1, 7
	s_mov_b32 s0, s6
	v_writelane_b32 v255, s0, 8
	s_mov_b32 s50, 0x20000
	s_mov_b32 s90, 0x30000
	v_writelane_b32 v255, s1, 9
	s_lshl_b64 s[0:1], s[6:7], 20
	v_writelane_b32 v255, s0, 10
	s_mov_b32 s83, 0x80000
	s_mov_b32 s64, 0x50000
	v_writelane_b32 v255, s1, 11
	s_mov_b32 s67, 0xd5800000
	s_lshl_b64 s[74:75], s[42:43], 12
	s_mov_b32 s53, -1
	s_mov_b32 s96, 0xbfb8aa3b
	s_mov_b32 s68, 0x3f317218
	s_mov_b32 s56, 0x3fb8aa3b
	s_mov_b32 s54, 0x3d800000
	s_mov_b64 s[72:73], s[70:71]
	s_mov_b32 s76, s85
	v_writelane_b32 v255, s91, 12
	s_branch .LBB0_205

; #define LAS __attribute__((address_space(3)))
; __device__ __forceinline__ void mixer_hg2(const Args& a, Frame& F, bool ctx_out) {
;     ...
;     const int lane = F.lane, w = F.wave, tid = F.tid, g = lane >> 4, i = lane & 15;
;     const int rg = w >> 1, cg = w & 1, nq0 = 16 * rg;
;     LAS unsigned char* const L = F.lds;
;     const bf16* act = (const bf16*)(a.ws + WS_ACT);
;     mx_bf16x8 bt0, bt1;
; #pragma unroll
;     for (int j = 0; j < 8; ++j) { bt0[j] = (8 * g + j <= i) ? (short)0x3F80 : (short)0; bt1[j] = (8 * g + j <= 16 + i) ? (short)0x3F80 : (short)0; }
;     for (int task = F.vcu; task < BATCH * NH * 2 * NEB; task += F.G) {
;         const int eb = task % NEB, dir = (task / NEB) & 1, h = (task / (2 * NEB)) % NH, b = task / (2 * NEB * NH);
;         bf16* O = (bf16*)(a.ws + (dir ? WS_OB : WS_OF));
;         const bf16* src0 = act;
;         const bf16* src1 = act + (size_t)(2 + 2 * dir) * ACT_STRIDE;
;         const bf16* src2 = act + (size_t)(1 + 2 * dir) * ACT_STRIDE;
;         const bf16* srcv = act + (size_t)5 * ACT_STRIDE;
;         const int vrow = tid & 63, vcc = tid >> 6, vs = dir ? 63 - vrow : vrow;
.LBB0_507:
	s_andn2_b64 vcc, exec, s[8:9]
	s_cbranch_vccnz .LBB0_570
	s_getreg_b32 s6, hwreg(HW_REG_HW_ID, 0, 6)
	s_lshl_b32 s6, s6, 2
	s_add_i32 s6, s6, 0
	s_add_i32 s6, s6, 0x20540
	v_mov_b32_e32 v0, s6
	ds_read_b32 v0, v0
	v_readlane_b32 s8, v254, 25
	v_mbcnt_lo_u32_b32 v3, -1, 0
	v_mbcnt_hi_u32_b32 v3, -1, v3
	v_readlane_b32 s9, v254, 26
	v_mov_b32_e32 v2, v1
	s_waitcnt lgkmcnt(0)
	v_readfirstlane_b32 s6, v0
	s_andn2_b64 vcc, exec, s[8:9]
	s_nop 0
	v_lshl_add_u32 v0, s6, 6, v3
	s_nop 0
	v_readfirstlane_b32 s6, v0
	s_cbranch_vccnz .LBB0_524
	s_waitcnt vmcnt(0)
	v_mov_b64_e32 v[4:5], s[0:1]
	flat_load_dwordx2 v[14:15], v[4:5] offset:152
	v_and_b32_e32 v18, 15, v0
	v_bfe_u32 v19, v0, 4, 2
	v_or_b32_e32 v11, 16, v18
	v_lshlrev_b32_e32 v12, 3, v19
	v_lshlrev_b32_e32 v8, 4, v0
	v_cmp_gt_u32_e32 vcc, v12, v11
	v_mov_b32_e32 v31, 0x3f80
	v_lshlrev_b32_e32 v6, 3, v0
	v_bfe_u32 v9, v0, 2, 2
	v_lshrrev_b32_e32 v10, 1, v0
	v_and_b32_e32 v186, 0xf0, v8
	v_cndmask_b32_e64 v8, v31, 0, vcc
	v_cmp_lt_u32_e32 vcc, v12, v11
	v_and_b32_e32 v184, 0x78, v6
	v_and_or_b32 v6, v10, 24, v9
	v_cndmask_b32_e32 v9, 0, v31, vcc
	v_cmp_gt_u32_e32 vcc, v12, v18
	v_and_b32_e32 v185, 63, v0
	s_ashr_i32 s6, s6, 6
	v_ashrrev_i32_e32 v7, 3, v0
	v_cndmask_b32_e64 v10, v31, 0, vcc
	v_cmp_lt_u32_e32 vcc, v12, v18
	v_or_b32_e32 v21, 2, v12
	v_and_b32_e32 v16, -8, v7
	s_lshl_b32 s9, s6, 5
	v_lshlrev_b32_e32 v7, 3, v185
	v_cndmask_b32_e32 v13, 0, v31, vcc
	v_or_b32_e32 v20, 3, v12
	v_cmp_gt_u32_e32 vcc, v21, v11
	v_and_or_b32 v27, v7, 16, s9
	v_and_b32_e32 v28, 8, v7
	s_mov_b32 s10, 0x5040100
	v_cndmask_b32_e64 v7, v31, 0, vcc
	v_cmp_gt_u32_e32 vcc, v20, v11
	v_mul_u32_u24_e32 v26, 0x120, v6
	v_perm_b32 v6, v9, v8, s10
	v_cndmask_b32_e64 v8, v31, 0, vcc
	v_cmp_gt_u32_e32 vcc, v21, v18
	v_or_b32_e32 v23, 4, v12
	v_or_b32_e32 v22, 5, v12
	v_cndmask_b32_e64 v9, v31, 0, vcc
	v_cmp_gt_u32_e32 vcc, v20, v18
	v_perm_b32 v10, v13, v10, s10
	v_or_b32_e32 v25, 6, v12
	v_cndmask_b32_e64 v13, v31, 0, vcc
	v_cmp_gt_u32_e32 vcc, v23, v11
	v_or_b32_e32 v24, 7, v12
	v_readlane_b32 s24, v254, 62
	v_cndmask_b32_e64 v20, v31, 0, vcc
	v_cmp_gt_u32_e32 vcc, v22, v11
	s_lshl_b32 s8, s6, 3
	s_add_i32 s6, s9, s24
	v_cndmask_b32_e64 v21, v31, 0, vcc
	v_cmp_gt_u32_e32 vcc, v23, v18
	s_add_i32 s7, s9, 0
	v_add3_u32 v26, 0, v26, v27
	v_cndmask_b32_e64 v23, v31, 0, vcc
	v_cmp_gt_u32_e32 vcc, v22, v18
	v_add_u32_e32 v27, s6, v12
	v_bfi_b32 v229, -16, s8, v0
	v_cndmask_b32_e64 v22, v31, 0, vcc
	v_cmp_gt_u32_e32 vcc, v25, v11
	s_movk_i32 s25, 0x120
	v_perm_b32 v7, v8, v7, s10
	v_cndmask_b32_e64 v29, v31, 0, vcc
	v_cmp_gt_u32_e32 vcc, v24, v11
	v_perm_b32 v8, v21, v20, s10
	v_and_b32_e32 v232, 48, v0
	v_cndmask_b32_e64 v30, v31, 0, vcc
	v_cmp_gt_u32_e32 vcc, v25, v18
	v_ashrrev_i32_e32 v237, 4, v0
	v_add_u32_e32 v0, 0x200, v0
	v_cndmask_b32_e64 v25, v31, 0, vcc
	v_cmp_gt_u32_e32 vcc, v24, v18
	v_perm_b32 v11, v13, v9, s10
	v_perm_b32 v9, v30, v29, s10
	v_cndmask_b32_e64 v24, v31, 0, vcc
	v_add_u32_e32 v31, s7, v12
	s_mov_b64 s[6:7], 0xd000000
	s_waitcnt vmcnt(0) lgkmcnt(0)
	v_lshl_add_u64 v[188:189], v[14:15], 0, s[6:7]
	s_mov_b64 s[6:7], 0x22400000
	v_lshl_add_u64 v[190:191], v[14:15], 0, s[6:7]
	v_mul_lo_u32 v14, v229, s25
	v_add_u32_e32 v230, 0, v14
	s_and_b32 s6, s9, 32
	v_lshlrev_b32_e32 v14, 2, v19
	v_or_b32_e32 v19, s6, v14
	v_or_b32_e32 v21, 2, v19
	v_cmp_gt_i32_e64 s[12:13], v21, v229
	v_or_b32_e32 v21, 3, v19
	v_cmp_gt_i32_e64 s[14:15], v21, v229
	v_lshlrev_b32_e32 v21, 7, v229
	v_sub_u32_e32 v233, v230, v21
	v_or_b32_e32 v21, 17, v19
	s_movk_i32 s7, 0x90
	v_perm_b32 v12, v22, v23, s10
	v_perm_b32 v13, v24, v25, s10
	v_or_b32_e32 v20, 16, v19
	v_cmp_gt_i32_e64 s[8:9], v19, v229
	v_cmp_lt_i32_e64 s[10:11], v19, v229
	v_lshlrev_b32_e32 v234, 1, v19
	v_cmp_gt_i32_e64 s[18:19], v21, v229
	v_or_b32_e32 v21, 18, v19
	v_or_b32_e32 v19, 19, v19
	v_ashrrev_i32_e32 v238, 4, v0
	v_mul_lo_u32 v0, v16, s7
	v_lshlrev_b32_e32 v187, 1, v185
	v_ashrrev_i32_e32 v17, 31, v16
	v_or_b32_e32 v15, s6, v18
	v_cmp_gt_i32_e64 s[22:23], v19, v229
	v_add_u32_e32 v241, 0, v0
	v_mul_u32_u24_e32 v19, 0x120, v18
	v_mad_u32_u24 v18, v18, s7, 0
	v_mov_b32_e32 v0, s24
	v_mov_b32_e32 v3, v2
	v_mov_b32_e32 v4, v2
	v_mov_b32_e32 v5, v2
	v_xor_b32_e32 v228, 0x7e, v187
	v_mad_u32_u24 v231, v15, s25, 0
	v_cmp_gt_i32_e64 s[16:17], v20, v229
	v_cmp_gt_i32_e64 s[20:21], v21, v229
	v_lshlrev_b32_e32 v235, 1, v20
	v_sub_u32_e32 v236, 63, v229
	v_sub_u32_e32 v239, 63, v237
	v_sub_u32_e32 v240, 63, v238
	v_mad_u32_u24 v242, v15, s25, v0
	v_mad_u32_u24 v243, v15, s7, 0
	v_lshlrev_b64 v[192:193], 1, v[16:17]
	s_lshl_b32 s28, s6, 1
	v_lshlrev_b32_e32 v0, 1, v14
	v_add_u32_e32 v244, v18, v232
	v_add_u32_e32 v245, v26, v28
	v_add_u32_e32 v246, v27, v19
	v_add_u32_e32 v247, v31, v19
	v_readlane_b32 s6, v254, 4
	s_branch .LBB0_511
; #define LAS __attribute__((address_space(3)))
; __device__ __forceinline__ void mixer_hg2(const Args& a, Frame& F, bool ctx_out) {
;     ...
;             H2_STAGE(u);
;             MX_BAR();
;             { const int cn = (c + PF < NCH) ? c + PF : NCH - 1; H2_LOAD(cn, u); }
;             f32x4 fe, fu;
;             {
;                 unsigned one2_ = 0x3F803F80u; asm volatile("" : "+v"(one2_));
;                 typedef unsigned u4_ __attribute__((ext_vector_type(4)));
;                 const mx_bf16x8 ones = __builtin_bit_cast(mx_bf16x8, (u4_){one2_, one2_, one2_, one2_});
;                 const mx_bf16x8 a0 = frag_tr(L + 2 * IMG, QS, 0, 16 * w, lane), a1 = frag_tr(L + 2 * IMG, QS, 32, 16 * w, lane);
;                 const f32x4 z = ZERO4;
;                 f32x4 ct[4];
;                 ct[0] = MX_MFMA(a0, bt0, z); ct[1] = MX_MFMA(a0, bt1, z);
;                 const f32x4 cref = MX_MFMA(a0, ones, z);
;                 ct[2] = MX_MFMA(a1, bt0, cref); ct[3] = MX_MFMA(a1, bt1, cref);
;                 const f32x4 cend = MX_MFMA(a1, ones, cref);
;                 fe = (f32x4){__expf(cend[0]), __expf(cend[1]), __expf(cend[2]), __expf(cend[3])};
;                 fu = (f32x4){__expf(cend[0] - cref[0]), __expf(cend[1] - cref[1]), __expf(cend[2] - cref[2]), __expf(cend[3] - cref[3])};
;                 const f32x4 fs = {__expf(cref[0]), __expf(cref[1]), __expf(cref[2]), __expf(cref[3])};
; #pragma unroll
;                 for (int te = 0; te < 4; ++te) { const f32x4 s = accS[te] * fs; v2u sw; sw.x = pk2(s[0], s[1]); sw.y = pk2(s[2], s[3]);
;                     *(LAS v2u*)(L + O_ST + (16 * te + i) * QS + (16 * w + 4 * g) * 2) = sw; }
; #pragma unroll
;                 for (int t = 0; t < 4; ++t) {
;                     LAS unsigned char* pq = L + (16 * t + i) * QS + (16 * w + 4 * g) * 2;
;                     const v2u qw = *(const LAS v2u*)pq, kw = *(const LAS v2u*)(pq + IMG);
;                     const f32x4 dd = ct[t] - cref;
;                     const f32x4 tt = (f32x4){__builtin_amdgcn_fmed3f(dd[0], -80.f, 80.f), __builtin_amdgcn_fmed3f(dd[1], -80.f, 80.f), __builtin_amdgcn_fmed3f(dd[2], -80.f, 80.f), __builtin_amdgcn_fmed3f(dd[3], -80.f, 80.f)} * 1.4426950408889634f;
;                     const f32x4 e1 = {__builtin_amdgcn_exp2f(tt[0]), __builtin_amdgcn_exp2f(tt[1]), __builtin_amdgcn_exp2f(tt[2]), __builtin_amdgcn_exp2f(tt[3])};
.LBB0_510:
	s_waitcnt vmcnt(4)
	ds_write_b128 v251, v[94:97]
	s_waitcnt vmcnt(3)
	ds_write_b128 v251, v[98:101] offset:18432
	ds_write_b128 v251, v[102:105] offset:36864
	ds_write_b128 v250, v[110:113]
	s_waitcnt vmcnt(2)
	ds_write_b128 v250, v[106:109] offset:18432
	s_waitcnt vmcnt(1)
	ds_write_b128 v250, v[114:117] offset:36864
	s_waitcnt vmcnt(0)
	ds_write_b16 v249, v118 offset:55296
	ds_write_b16_d16_hi v249, v118 offset:55440
	ds_write_b16 v249, v119 offset:55584
	ds_write_b16_d16_hi v249, v119 offset:55728
	ds_write_b16 v249, v120 offset:55872
	ds_write_b16_d16_hi v249, v120 offset:56016
	ds_write_b16 v249, v121 offset:56160
	ds_write_b16_d16_hi v249, v121 offset:56304
	v_mov_b32_e32 v14, 0x3f803f80
	s_waitcnt lgkmcnt(0)
	s_barrier
	ds_read_b64_tr_b16 v[18:19], v245 offset:36864
	ds_read_b64_tr_b16 v[20:21], v245 offset:38016
	ds_read_b64_tr_b16 v[30:31], v245 offset:46080
	ds_read_b64_tr_b16 v[32:33], v245 offset:47232
	v_mov_b32_e32 v15, v14
	v_mov_b32_e32 v16, v14
	v_mov_b32_e32 v17, v14
	s_waitcnt lgkmcnt(2)
	v_mfma_f32_16x16x32_bf16 v[34:37], v[18:21], v[10:13], v[2:5]
	v_add_u32_e32 v54, v231, v232
	s_and_b64 s[24:25], s[24:25], exec
	s_cselect_b32 s24, 0xfc0, 0
	v_mfma_f32_16x16x32_bf16 v[14:17], v[18:21], v[14:17], v[2:5]
	s_or_b32 s7, s24, s7
	v_mfma_f32_16x16x32_bf16 v[26:29], v[18:21], v[6:9], v[2:5]
	s_waitcnt lgkmcnt(0)
	v_mfma_f32_16x16x32_bf16 v[22:25], v[30:33], v[10:13], v[14:17]
	s_nop 3
	v_mul_f32_e32 v18, 0x3fb8aa3b, v14
	v_mul_f32_e32 v19, 0x3fb8aa3b, v16
	v_exp_f32_e32 v38, v18
	v_mul_f32_e32 v18, 0x3fb8aa3b, v15
	v_exp_f32_e32 v40, v19
	v_mul_f32_e32 v19, 0x3fb8aa3b, v17
	v_exp_f32_e32 v41, v19
	v_exp_f32_e32 v39, v18
	v_mfma_f32_16x16x32_bf16 v[18:21], v[30:33], v[6:9], v[14:17]
	v_sub_f32_e32 v37, v37, v17
	v_pk_mul_f32 v[30:31], v[218:219], v[40:41]
	v_pk_mul_f32 v[32:33], v[214:215], v[38:39]
	v_sub_f32_e32 v36, v36, v16
	v_cvt_pk_bf16_f32 v32, v32, v33
	v_cvt_pk_bf16_f32 v33, v30, v31
	ds_write_b64 v246, v[32:33]
	v_pk_mul_f32 v[30:31], v[212:213], v[40:41]
	v_pk_mul_f32 v[32:33], v[210:211], v[38:39]
	v_sub_f32_e32 v35, v35, v15
	v_cvt_pk_bf16_f32 v32, v32, v33
	v_cvt_pk_bf16_f32 v33, v30, v31
	ds_write_b64 v246, v[32:33] offset:4608
	v_pk_mul_f32 v[30:31], v[208:209], v[40:41]
	v_pk_mul_f32 v[32:33], v[206:207], v[38:39]
	v_sub_f32_e32 v34, v34, v14
	v_cvt_pk_bf16_f32 v32, v32, v33
	v_cvt_pk_bf16_f32 v33, v30, v31
	v_med3_f32 v34, v34, s95, v182
	v_med3_f32 v35, v35, s95, v182
	v_med3_f32 v36, v36, s95, v182
	v_med3_f32 v37, v37, s95, v182
	ds_write_b64 v246, v[32:33] offset:9216
	v_pk_mul_f32 v[30:31], v[204:205], v[40:41]
	v_pk_mul_f32 v[32:33], v[202:203], v[38:39]
	v_pk_mul_f32 v[36:37], v[36:37], s[56:57] op_sel_hi:[1,0]
	v_pk_mul_f32 v[34:35], v[34:35], s[56:57] op_sel_hi:[1,0]
	v_cvt_pk_bf16_f32 v32, v32, v33
	v_cvt_pk_bf16_f32 v33, v30, v31
	v_exp_f32_e32 v34, v34
	v_exp_f32_e32 v35, v35
	v_exp_f32_e32 v36, v36
	v_exp_f32_e32 v37, v37
	ds_write_b64 v246, v[32:33] offset:13824
	ds_read_b64 v[30:31], v247
	ds_read_b64 v[32:33], v247 offset:18432
	v_sub_f32_e32 v29, v29, v17
	v_sub_f32_e32 v28, v28, v16
	v_sub_f32_e32 v27, v27, v15
	v_sub_f32_e32 v26, v26, v14
	v_rcp_f32_e32 v38, v34
	v_rcp_f32_e32 v39, v35
	v_rcp_f32_e32 v40, v36
	v_rcp_f32_e32 v41, v37
	v_med3_f32 v26, v26, s95, v182
	v_med3_f32 v27, v27, s95, v182
	v_med3_f32 v28, v28, s95, v182
	v_med3_f32 v29, v29, s95, v182
	v_pk_mul_f32 v[28:29], v[28:29], s[56:57] op_sel_hi:[1,0]
	v_pk_mul_f32 v[26:27], v[26:27], s[56:57] op_sel_hi:[1,0]
	v_exp_f32_e32 v28, v28
	v_exp_f32_e32 v26, v26
	v_exp_f32_e32 v27, v27
	v_exp_f32_e32 v29, v29
	s_waitcnt lgkmcnt(1)
	v_lshlrev_b32_e32 v48, 16, v30
	v_and_b32_e32 v49, 0xffff0000, v30
	v_lshlrev_b32_e32 v30, 16, v31
	v_and_b32_e32 v31, 0xffff0000, v31
	s_waitcnt lgkmcnt(0)
	v_lshlrev_b32_e32 v52, 16, v32
	v_and_b32_e32 v53, 0xffff0000, v32
	v_lshlrev_b32_e32 v32, 16, v33
	v_and_b32_e32 v33, 0xffff0000, v33
	v_pk_mul_f32 v[30:31], v[36:37], v[30:31]
	v_pk_mul_f32 v[34:35], v[34:35], v[48:49]
	v_pk_mul_f32 v[32:33], v[40:41], v[32:33]
	v_pk_mul_f32 v[38:39], v[38:39], v[52:53]
	ds_read_b64 v[42:43], v247 offset:4608
	ds_read_b64 v[44:45], v247 offset:9216
	ds_read_b64 v[46:47], v247 offset:13824
	v_cvt_pk_bf16_f32 v34, v34, v35
	v_cvt_pk_bf16_f32 v35, v30, v31
	v_cvt_pk_bf16_f32 v30, v38, v39
	v_cvt_pk_bf16_f32 v31, v32, v33
	v_sub_f32_e32 v25, v25, v17
	v_sub_f32_e32 v24, v24, v16
	v_sub_f32_e32 v23, v23, v15
	v_sub_f32_e32 v22, v22, v14
	ds_read_b64 v[36:37], v247 offset:23040
	ds_read_b64 v[48:49], v247 offset:27648
	ds_read_b64 v[50:51], v247 offset:32256
	ds_write_b64 v247, v[34:35]
	ds_write_b64 v247, v[30:31] offset:18432
	v_rcp_f32_e32 v30, v26
	v_rcp_f32_e32 v31, v27
	v_rcp_f32_e32 v32, v28
	v_rcp_f32_e32 v33, v29
	v_med3_f32 v22, v22, s95, v182
	v_med3_f32 v23, v23, s95, v182
	v_med3_f32 v24, v24, s95, v182
	v_med3_f32 v25, v25, s95, v182
	v_pk_mul_f32 v[24:25], v[24:25], s[56:57] op_sel_hi:[1,0]
	v_pk_mul_f32 v[22:23], v[22:23], s[56:57] op_sel_hi:[1,0]
	s_waitcnt lgkmcnt(7)
	v_lshlrev_b32_e32 v34, 16, v42
	v_and_b32_e32 v35, 0xffff0000, v42
	v_exp_f32_e32 v22, v22
	v_exp_f32_e32 v23, v23
	v_exp_f32_e32 v24, v24
	v_exp_f32_e32 v25, v25
	v_lshlrev_b32_e32 v38, 16, v43
	v_and_b32_e32 v39, 0xffff0000, v43
	v_pk_mul_f32 v[26:27], v[26:27], v[34:35]
	s_waitcnt lgkmcnt(4)
; __device__ __forceinline__ void mixer_hg2(const Args& a, Frame& F, bool ctx_out) {
;     ...
;             MX_BAR();
;             const int rlo = H2_ROWLO(c);
;             const bool do_out = ctx_out || c >= NCTX;
;             mx_bf16x8 aq[KS];
;             {
;                 mx_bf16x8 kf[2][KS], vt[4][2];
;                 if (do_out) {
; #pragma unroll
;                     for (int ks = 0; ks < KS; ++ks) { aq[ks] = frag_row(L, QS, nq0, 32 * ks, lane); kf[0][ks] = frag_row(L + IMG, QS, 32 * cg, 32 * ks, lane); kf[1][ks] = frag_row(L + IMG, QS, 32 * cg + 16, 32 * ks, lane); }
;                 }
; #pragma unroll
;                 for (int te = 0; te < 4; ++te) { vt[te][0] = frag_row8(L + O_VT, 16 * te, 0, lane); vt[te][1] = frag_row8(L + O_VT, 16 * te, 32, lane); }
;                 const mx_bf16x8 ak0 = frag_tr(L + IMG, QS, 0, 16 * w, lane), ak1 = frag_tr(L + IMG, QS, 32, 16 * w, lane);
;                 __builtin_amdgcn_sched_barrier(0);
;                 f32x4 pt0 = ZERO4, pt1 = ZERO4;
;                 if (do_out) {
; #pragma unroll
;                     for (int ks = 0; ks < KS; ++ks) { pt0 = MX_MFMA(kf[0][ks], aq[ks], pt0); pt1 = MX_MFMA(kf[1][ks], aq[ks], pt1); }
;                 }
;                 f32x4 uu[4];
; #pragma unroll
;                 for (int te = 0; te < 4; ++te) { const f32x4 z4 = ZERO4; uu[te] = MX_MFMA(ak0, vt[te][0], z4); }
; #pragma unroll
;                 for (int te = 0; te < 4; ++te) uu[te] = MX_MFMA(ak1, vt[te][1], uu[te]);
;                 __builtin_amdgcn_sched_barrier(0);
;                 if (do_out) {
;                     const int m0 = 32 * cg + 4 * g, m1 = m0 + 16, n = nq0 + i;
;                     v2u pw; pw.x = pk2((m0 <= n) ? pt0[0] : 0.f, (m0 + 1 <= n) ? pt0[1] : 0.f); pw.y = pk2((m0 + 2 <= n) ? pt0[2] : 0.f, (m0 + 3 <= n) ? pt0[3] : 0.f);
;                     *(LAS v2u*)(L + O_P + n * PS + m0 * 2) = pw;
;                     pw.x = pk2((m1 <= n) ? pt1[0] : 0.f, (m1 + 1 <= n) ? pt1[1] : 0.f); pw.y = pk2((m1 + 2 <= n) ? pt1[2] : 0.f, (m1 + 3 <= n) ? pt1[3] : 0.f);
;                     *(LAS v2u*)(L + O_P + n * PS + m1 * 2) = pw;
;                 }
; #pragma unroll
;                 for (int te = 0; te < 4; ++te) accS[te] = accS[te] * fe + uu[te] * fu;
;             }
;             mx_bf16x8 st[2][KS], vo[2][2];
;             if (do_out) {
; #pragma unroll
;                 for (int te = 0; te < 2; ++te)
	v_lshlrev_b32_e32 v34, 16, v36
	v_and_b32_e32 v35, 0xffff0000, v36
	v_lshlrev_b32_e32 v36, 16, v37
	v_and_b32_e32 v37, 0xffff0000, v37
	v_sub_f32_e32 v17, v21, v17
	v_sub_f32_e32 v16, v20, v16
	v_sub_f32_e32 v15, v19, v15
	v_sub_f32_e32 v14, v18, v14
	v_pk_mul_f32 v[28:29], v[28:29], v[38:39]
	v_pk_mul_f32 v[32:33], v[32:33], v[36:37]
	v_pk_mul_f32 v[30:31], v[30:31], v[34:35]
	v_med3_f32 v14, v14, s95, v182
	v_med3_f32 v15, v15, s95, v182
	v_med3_f32 v16, v16, s95, v182
	v_med3_f32 v17, v17, s95, v182
	v_cvt_pk_bf16_f32 v26, v26, v27
	v_cvt_pk_bf16_f32 v27, v28, v29
	v_cvt_pk_bf16_f32 v28, v30, v31
	v_cvt_pk_bf16_f32 v29, v32, v33
	v_pk_mul_f32 v[16:17], v[16:17], s[56:57] op_sel_hi:[1,0]
	v_pk_mul_f32 v[14:15], v[14:15], s[56:57] op_sel_hi:[1,0]
	ds_write_b64 v247, v[26:27] offset:4608
	ds_write_b64 v247, v[28:29] offset:23040
	v_rcp_f32_e32 v26, v22
	v_rcp_f32_e32 v27, v23
	v_rcp_f32_e32 v28, v24
	v_rcp_f32_e32 v29, v25
	v_exp_f32_e32 v14, v14
	v_exp_f32_e32 v15, v15
	v_exp_f32_e32 v16, v16
	v_exp_f32_e32 v17, v17
	v_lshlrev_b32_e32 v30, 16, v44
	v_and_b32_e32 v31, 0xffff0000, v44
	v_lshlrev_b32_e32 v32, 16, v45
	v_and_b32_e32 v33, 0xffff0000, v45
	v_pk_mul_f32 v[24:25], v[24:25], v[32:33]
	v_pk_mul_f32 v[22:23], v[22:23], v[30:31]
	s_waitcnt lgkmcnt(5)
	v_lshlrev_b32_e32 v30, 16, v48
	v_and_b32_e32 v31, 0xffff0000, v48
	v_lshlrev_b32_e32 v32, 16, v49
	v_and_b32_e32 v33, 0xffff0000, v49
	v_pk_mul_f32 v[28:29], v[28:29], v[32:33]
	v_pk_mul_f32 v[26:27], v[26:27], v[30:31]
	v_rcp_f32_e32 v18, v14
	v_rcp_f32_e32 v19, v15
	v_rcp_f32_e32 v20, v16
	v_rcp_f32_e32 v21, v17
	v_cvt_pk_bf16_f32 v22, v22, v23
	v_cvt_pk_bf16_f32 v23, v24, v25
	v_cvt_pk_bf16_f32 v24, v26, v27
	v_cvt_pk_bf16_f32 v25, v28, v29
	ds_write_b64 v247, v[22:23] offset:9216
	ds_write_b64 v247, v[24:25] offset:27648
	v_lshlrev_b32_e32 v22, 16, v46
	v_and_b32_e32 v23, 0xffff0000, v46
	v_lshlrev_b32_e32 v24, 16, v47
	v_and_b32_e32 v25, 0xffff0000, v47
	v_pk_mul_f32 v[16:17], v[16:17], v[24:25]
	v_pk_mul_f32 v[14:15], v[14:15], v[22:23]
	s_waitcnt lgkmcnt(6)
	v_lshlrev_b32_e32 v22, 16, v50
	v_and_b32_e32 v23, 0xffff0000, v50
	v_lshlrev_b32_e32 v24, 16, v51
	v_and_b32_e32 v25, 0xffff0000, v51
	v_pk_mul_f32 v[20:21], v[20:21], v[24:25]
	v_pk_mul_f32 v[18:19], v[18:19], v[22:23]
	v_cvt_pk_bf16_f32 v14, v14, v15
	v_cvt_pk_bf16_f32 v15, v16, v17
	v_cvt_pk_bf16_f32 v16, v18, v19
	v_cvt_pk_bf16_f32 v17, v20, v21
	ds_write_b64 v247, v[14:15] offset:13824
	ds_write_b64 v247, v[16:17] offset:32256
	s_waitcnt lgkmcnt(0)
	s_barrier
	v_add_u32_e32 v42, v230, v232
	ds_read_b128 v[14:17], v42
	ds_read_b128 v[18:21], v42 offset:64
	ds_read_b128 v[30:33], v54 offset:18432
	ds_read_b128 v[38:41], v54 offset:18496
	ds_read_b128 v[26:29], v54 offset:23040
	ds_read_b128 v[34:37], v54 offset:23104
	ds_read_b128 v[22:25], v42 offset:128
	ds_read_b128 v[42:45], v42 offset:192
	ds_read_b128 v[50:53], v54 offset:18560
	ds_read_b128 v[58:61], v54 offset:18624
	ds_read_b128 v[46:49], v54 offset:23168
	ds_read_b128 v[54:57], v54 offset:23232
	s_waitcnt lgkmcnt(9)
	v_mfma_f32_16x16x32_bf16 v[62:65], v[30:33], v[14:17], v[2:5]
	s_waitcnt lgkmcnt(7)
	v_mfma_f32_16x16x32_bf16 v[66:69], v[26:29], v[14:17], v[2:5]
	v_mfma_f32_16x16x32_bf16 v[62:65], v[38:41], v[18:21], v[62:65]
	s_waitcnt lgkmcnt(6)
	v_mfma_f32_16x16x32_bf16 v[66:69], v[34:37], v[18:21], v[66:69]
	s_waitcnt lgkmcnt(3)
	v_mfma_f32_16x16x32_bf16 v[62:65], v[50:53], v[22:25], v[62:65]
	s_waitcnt lgkmcnt(1)
	v_mfma_f32_16x16x32_bf16 v[66:69], v[46:49], v[22:25], v[66:69]
	v_mfma_f32_16x16x32_bf16 v[62:65], v[58:61], v[42:45], v[62:65]
	s_waitcnt lgkmcnt(0)
	v_mfma_f32_16x16x32_bf16 v[66:69], v[54:57], v[42:45], v[66:69]
	s_nop 5
	v_cndmask_b32_e64 v62, v62, 0, s[8:9]
	v_cndmask_b32_e64 v63, 0, v63, s[10:11]
	v_cvt_pk_bf16_f32 v62, v62, v63
	v_cndmask_b32_e64 v63, v64, 0, s[12:13]
	v_cndmask_b32_e64 v64, v65, 0, s[14:15]
	v_cvt_pk_bf16_f32 v63, v63, v64
	v_add_u32_e32 v64, v233, v234
	ds_write_b64 v64, v[62:63] offset:64512
	v_cndmask_b32_e64 v62, v66, 0, s[16:17]
	v_cndmask_b32_e64 v63, v67, 0, s[18:19]
	v_cvt_pk_bf16_f32 v62, v62, v63
	v_cndmask_b32_e64 v63, v68, 0, s[20:21]
	v_cndmask_b32_e64 v64, v69, 0, s[22:23]
	v_cvt_pk_bf16_f32 v63, v63, v64
	v_add_u32_e32 v64, v233, v235
	ds_write_b64 v64, v[62:63] offset:64512
	v_add_u32_e32 v90, v242, v232
	ds_read_b128 v[62:65], v90
	ds_read_b128 v[66:69], v90 offset:64
	ds_read_b128 v[70:73], v90 offset:128
	ds_read_b128 v[74:77], v90 offset:192
	ds_read_b128 v[78:81], v90 offset:4608
	ds_read_b128 v[82:85], v90 offset:4672
	ds_read_b128 v[86:89], v90 offset:4736
	ds_read_b128 v[90:93], v90 offset:4800
	s_waitcnt lgkmcnt(0)
	s_barrier
	v_add_u32_e32 v98, v233, v232
	v_add_u32_e32 v114, v243, v232
	ds_read_b128 v[94:97], v98 offset:64512
	ds_read_b128 v[98:101], v98 offset:64576
	ds_read_b128 v[102:105], v114 offset:55296
	ds_read_b128 v[106:109], v114 offset:55360
	ds_read_b128 v[110:113], v114 offset:57600
	ds_read_b128 v[114:117], v114 offset:57664
	s_waitcnt lgkmcnt(3)
	v_mfma_f32_16x16x32_bf16 v[102:105], v[102:105], v[94:97], v[2:5]
	s_add_i32 s6, s6, s3
	s_cmpk_gt_i32 s6, 0xff
	s_waitcnt lgkmcnt(1)
	v_mfma_f32_16x16x32_bf16 v[94:97], v[110:113], v[94:97], v[2:5]
	v_add_u32_e32 v110, s7, v248
	v_ashrrev_i32_e32 v111, 31, v110
	v_lshlrev_b64 v[110:111], 12, v[110:111]
	v_mfma_f32_16x16x32_bf16 v[102:105], v[62:65], v[14:17], v[102:105]
	v_mfma_f32_16x16x32_bf16 v[94:97], v[78:81], v[14:17], v[94:97]
	v_mfma_f32_16x16x32_bf16 v[102:105], v[66:69], v[18:21], v[102:105]
	v_mfma_f32_16x16x32_bf16 v[94:97], v[82:85], v[18:21], v[94:97]
	v_mfma_f32_16x16x32_bf16 v[102:105], v[70:73], v[22:25], v[102:105]
	v_mfma_f32_16x16x32_bf16 v[94:97], v[86:89], v[22:25], v[94:97]
	v_mfma_f32_16x16x32_bf16 v[102:105], v[74:77], v[42:45], v[102:105]
	v_mfma_f32_16x16x32_bf16 v[94:97], v[90:93], v[42:45], v[94:97]
	v_mfma_f32_16x16x32_bf16 v[102:105], v[106:109], v[98:101], v[102:105]
	v_lshl_add_u64 v[106:107], v[194:195], 0, v[110:111]
	s_waitcnt lgkmcnt(0)
	v_mfma_f32_16x16x32_bf16 v[94:97], v[114:117], v[98:101], v[94:97]
	s_nop 4
	v_cvt_pk_bf16_f32 v102, v102, v103
	v_cvt_pk_bf16_f32 v103, v104, v105
	s_nop 0
	v_cvt_pk_bf16_f32 v94, v94, v95
	v_cvt_pk_bf16_f32 v95, v96, v97
	global_store_dwordx2 v[106:107], v[102:103], off
	global_store_dwordx2 v[106:107], v[94:95], off offset:32
	s_waitcnt lgkmcnt(0)
	s_barrier
	s_cbranch_scc1 .LBB0_524
; #define MX_BAR() do { asm volatile("s_waitcnt lgkmcnt(0)" ::: "memory"); __builtin_amdgcn_s_barrier(); if (MXP_BAR > 1) __builtin_amdgcn_s_barrier(); asm volatile("" ::: "memory"); } while (0)
; __device__ __forceinline__ void mixer_hg2(const Args& a, Frame& F, bool ctx_out) {
;     ...
;     for (int task = F.vcu; task < BATCH * NH * 2 * NEB; task += F.G) {
;         const int eb = task % NEB, dir = (task / NEB) & 1, h = (task / (2 * NEB)) % NH, b = task / (2 * NEB * NH);
;         bf16* O = (bf16*)(a.ws + (dir ? WS_OB : WS_OF));
;         const bf16* src0 = act;
;         const bf16* src1 = act + (size_t)(2 + 2 * dir) * ACT_STRIDE;
;         const bf16* src2 = act + (size_t)(1 + 2 * dir) * ACT_STRIDE;
;         const bf16* srcv = act + (size_t)5 * ACT_STRIDE;
;         const int vrow = tid & 63, vcc = tid >> 6, vs = dir ? 63 - vrow : vrow;
;         f32x4 accS[4];
; #pragma unroll
;         for (int te = 0; te < 4; ++te) accS[te] = ZERO4;
;         constexpr int PF = MX_PF_HG;
;         static_assert(NCH % PF == 0, "prefetch depth must divide the chunk count");
;         v4u rq[PF][3][2]; v4u rv[PF];
;     ...
;         __syncthreads();
; #pragma unroll
;         for (int u = 0; u < PF; ++u) H2_LOAD(u, u);
;         for (int c0 = 0; c0 < NCH; c0 += PF)
; #pragma unroll
;         for (int u = 0; u < PF; ++u) {
;             const int c = c0 + u;
;             H2_STAGE(u);
;             MX_BAR();
;             { const int cn = (c + PF < NCH) ? c + PF : NCH - 1; H2_LOAD(cn, u); }
.LBB0_511:
	s_lshr_b32 s7, s6, 31
	s_add_i32 s7, s6, s7
	s_ashr_i32 s24, s7, 1
	s_ashr_i32 s33, s6, 31
	s_bfe_i32 s29, s24, 0x10000
	s_and_b32 s31, s24, 1
	s_lshr_b32 s24, s33, 30
	s_add_i32 s24, s6, s24
	s_ashr_i32 s25, s24, 2
	s_ashr_i32 s24, s24, 31
	s_lshr_b32 s24, s24, 28
	s_add_i32 s24, s25, s24
	s_and_b32 s24, s24, 0x1fffff0
	s_sub_i32 s34, s25, s24
	s_cmp_eq_u32 s31, 0
	s_cselect_b64 s[24:25], -1, 0
	s_and_b64 s[26:27], s[24:25], exec
	v_mov_b64_e32 v[94:95], s[0:1]
	s_mov_b32 s26, 0x2ac00000
	s_mul_i32 s84, s31, 0x8800000
	flat_load_dwordx2 v[122:123], v[94:95] offset:152
	s_cselect_b32 s30, s26, 0x33400000
	v_lshl_add_u64 v[94:95], v[188:189], 0, s[84:85]
	s_mov_b64 s[26:27], 0x8800000
	v_lshl_add_u64 v[196:197], v[94:95], 0, s[26:27]
	s_lshr_b32 s26, s33, 26
	s_add_i32 s26, s6, s26
	s_ashr_i32 s36, s26, 6
	s_mov_b64 s[26:27], 0x4400000
	s_lshl_b32 s33, s36, 8
	v_lshl_add_u64 v[198:199], v[94:95], 0, s[26:27]
	s_addk_i32 s33, 0x4000
	s_and_b32 s26, s29, 0xc0
	s_or_b32 s29, s26, s33
	s_lshl_b32 s26, s34, 7
	v_add_u32_e32 v94, s29, v237
	v_add_u32_e32 v104, s29, v238
	s_and_b32 s7, s7, 0x3fffffe
	v_or_b32_e32 v118, s29, v185
	s_ashr_i32 s27, s26, 31
	v_ashrrev_i32_e32 v95, 31, v94
	v_ashrrev_i32_e32 v105, 31, v104
	s_sub_i32 s7, s6, s7
	v_ashrrev_i32_e32 v119, 31, v118
	v_mov_b32_e32 v201, s27
	v_or_b32_e32 v200, s26, v184
	v_lshlrev_b64 v[94:95], 11, v[94:95]
	v_lshlrev_b64 v[104:105], 11, v[104:105]
	v_lshlrev_b64 v[118:119], 12, v[118:119]
	s_lshl_b32 s34, s7, 6
	v_lshl_add_u64 v[94:95], v[94:95], 0, v[200:201]
	v_lshl_add_u64 v[104:105], v[104:105], 0, v[200:201]
	v_lshl_add_u64 v[118:119], v[190:191], 0, v[118:119]
	s_lshl_b64 s[26:27], s[26:27], 1
	s_ashr_i32 s35, s34, 31
	v_lshlrev_b64 v[102:103], 1, v[94:95]
	v_lshlrev_b64 v[106:107], 1, v[104:105]
	v_lshl_add_u64 v[118:119], v[118:119], 0, s[26:27]
	s_lshl_b64 s[34:35], s[34:35], 1
	v_lshl_add_u64 v[94:95], v[188:189], 0, v[102:103]
	v_lshl_add_u64 v[98:99], v[196:197], 0, v[102:103]
	v_lshl_add_u64 v[102:103], v[198:199], 0, v[102:103]
	v_lshl_add_u64 v[108:109], v[188:189], 0, v[106:107]
	v_lshl_add_u64 v[118:119], v[118:119], 0, s[34:35]
	s_waitcnt lgkmcnt(0)
	s_barrier
	global_load_dwordx4 v[94:97], v[94:95], off
	s_nop 0
	global_load_dwordx4 v[98:101], v[98:99], off
	s_nop 0
	global_load_dwordx4 v[102:105], v[102:103], off
	s_nop 0
	global_load_dwordx4 v[110:113], v[108:109], off
	v_lshl_add_u64 v[108:109], v[196:197], 0, v[106:107]
	v_lshl_add_u64 v[114:115], v[198:199], 0, v[106:107]
	v_lshl_add_u64 v[118:119], v[118:119], 0, v[192:193]
	global_load_dwordx4 v[106:109], v[108:109], off
	s_nop 0
	global_load_dwordx4 v[114:117], v[114:115], off
	s_mov_b32 s31, 0
	global_load_dwordx4 v[118:121], v[118:119], off
	s_mov_b32 s29, s85
	v_lshl_add_u64 v[124:125], v[190:191], 0, s[26:27]
	v_lshl_add_u64 v[124:125], v[124:125], 0, s[34:35]
	v_cndmask_b32_e64 v126, v228, v187, s[24:25]
	v_lshl_add_u64 v[216:217], v[124:125], 0, v[192:193]
	v_cndmask_b32_e64 v248, v236, v229, s[24:25]
	s_lshl_b32 s7, s36, 12
	v_add_u32_e32 v249, v241, v126
	v_mov_b32_e32 v202, v2
	v_mov_b32_e32 v203, v2
	v_mov_b32_e32 v204, v2
	v_mov_b32_e32 v205, v2
	v_mov_b32_e32 v206, v2
	v_mov_b32_e32 v207, v2
	v_mov_b32_e32 v208, v2
	v_mov_b32_e32 v209, v2
	v_mov_b32_e32 v210, v2
	v_mov_b32_e32 v211, v2
	v_mov_b32_e32 v212, v2
	v_mov_b32_e32 v213, v2
	v_mov_b32_e32 v214, v2
	v_mov_b32_e32 v215, v2
	v_mov_b32_e32 v218, v2
	v_mov_b32_e32 v219, v2
	s_waitcnt vmcnt(0)
	v_lshl_add_u64 v[122:123], v[122:123], 0, s[30:31]
	v_lshl_add_u64 v[122:123], v[122:123], 0, s[26:27]
	v_lshl_add_u64 v[122:123], v[122:123], 0, s[34:35]
	v_lshl_add_u64 v[122:123], v[122:123], 0, s[28:29]
	v_lshl_add_u64 v[194:195], v[122:123], 0, v[0:1]
	v_cndmask_b32_e64 v122, v239, v237, s[24:25]
	s_movk_i32 s29, 0x120
	v_mad_u64_u32 v[122:123], s[26:27], v122, s29, v[186:187]
	v_cndmask_b32_e64 v123, v240, v238, s[24:25]
	v_mad_u64_u32 v[124:125], s[26:27], v123, s29, v[186:187]
	s_movk_i32 s30, 0x43
	v_add_u32_e32 v251, 0, v122
	v_add_u32_e32 v250, 0, v124
.LBB0_512:
	s_add_i32 s29, s31, 1
	s_add_i32 s36, s30, -1
	v_sub_co_u32_e64 v122, s[34:35], s31, 3
	s_and_b64 s[26:27], s[24:25], exec
	v_readfirstlane_b32 s26, v122
	s_cselect_b32 s26, s26, s36
	s_lshl_b32 s37, s26, 6
	s_add_i32 s40, s30, 0xffffffbf
	s_and_b64 s[26:27], s[24:25], exec
	s_cselect_b32 s26, s29, s40
	s_lshl_b32 s26, s26, 6
	s_add_i32 s40, s26, s33
	s_cmp_gt_u32 s31, 3
	s_cselect_b64 s[26:27], -1, 0
	s_add_i32 s37, s37, s7
	s_and_b64 s[34:35], s[34:35], exec
	s_cselect_b32 s34, s40, s37
	s_waitcnt vmcnt(4)
	ds_write_b128 v251, v[94:97]
	s_waitcnt vmcnt(3)
	ds_write_b128 v251, v[98:101] offset:18432
	ds_write_b128 v251, v[102:105] offset:36864
	ds_write_b128 v250, v[110:113]
	s_waitcnt vmcnt(2)
	ds_write_b128 v250, v[106:109] offset:18432
	s_waitcnt vmcnt(1)
	ds_write_b128 v250, v[114:117] offset:36864
	s_waitcnt vmcnt(0)
	ds_write_b16 v249, v118 offset:55296
	ds_write_b16_d16_hi v249, v118 offset:55440
	ds_write_b16 v249, v119 offset:55584
	ds_write_b16_d16_hi v249, v119 offset:55728
	ds_write_b16 v249, v120 offset:55872
	ds_write_b16_d16_hi v249, v120 offset:56016
	ds_write_b16 v249, v121 offset:56160
	ds_write_b16_d16_hi v249, v121 offset:56304
	v_add_u32_e32 v94, s34, v237
	v_add_u32_e32 v106, s34, v238
	v_ashrrev_i32_e32 v95, 31, v94
	v_ashrrev_i32_e32 v107, 31, v106
	v_lshlrev_b64 v[94:95], 11, v[94:95]
	v_lshlrev_b64 v[106:107], 11, v[106:107]
	v_lshl_add_u64 v[94:95], v[94:95], 0, v[200:201]
	v_lshl_add_u64 v[106:107], v[106:107], 0, v[200:201]
	v_or_b32_e32 v118, s34, v185
	v_lshlrev_b64 v[102:103], 1, v[94:95]
	v_lshlrev_b64 v[114:115], 1, v[106:107]
	v_ashrrev_i32_e32 v119, 31, v118
	s_waitcnt lgkmcnt(0)
	s_barrier
; #define LAS __attribute__((address_space(3)))
; __device__ __forceinline__ void mixer_hg2(const Args& a, Frame& F, bool ctx_out) {
;     ...
;             { const int cn = (c + PF < NCH) ? c + PF : NCH - 1; H2_LOAD(cn, u); }
;             f32x4 fe, fu;
;             {
;                 unsigned one2_ = 0x3F803F80u; asm volatile("" : "+v"(one2_));
;                 typedef unsigned u4_ __attribute__((ext_vector_type(4)));
;                 const mx_bf16x8 ones = __builtin_bit_cast(mx_bf16x8, (u4_){one2_, one2_, one2_, one2_});
;                 const mx_bf16x8 a0 = frag_tr(L + 2 * IMG, QS, 0, 16 * w, lane), a1 = frag_tr(L + 2 * IMG, QS, 32, 16 * w, lane);
;                 const f32x4 z = ZERO4;
;                 f32x4 ct[4];
;                 ct[0] = MX_MFMA(a0, bt0, z); ct[1] = MX_MFMA(a0, bt1, z);
;                 const f32x4 cref = MX_MFMA(a0, ones, z);
;                 ct[2] = MX_MFMA(a1, bt0, cref); ct[3] = MX_MFMA(a1, bt1, cref);
;                 const f32x4 cend = MX_MFMA(a1, ones, cref);
;                 fe = (f32x4){__expf(cend[0]), __expf(cend[1]), __expf(cend[2]), __expf(cend[3])};
;                 fu = (f32x4){__expf(cend[0] - cref[0]), __expf(cend[1] - cref[1]), __expf(cend[2] - cref[2]), __expf(cend[3] - cref[3])};
;                 const f32x4 fs = {__expf(cref[0]), __expf(cref[1]), __expf(cref[2]), __expf(cref[3])};
; #pragma unroll
;                 for (int te = 0; te < 4; ++te) { const f32x4 s = accS[te] * fs; v2u sw; sw.x = pk2(s[0], s[1]); sw.y = pk2(s[2], s[3]);
;                     *(LAS v2u*)(L + O_ST + (16 * te + i) * QS + (16 * w + 4 * g) * 2) = sw; }
; #pragma unroll
;                 for (int t = 0; t < 4; ++t) {
;                     LAS unsigned char* pq = L + (16 * t + i) * QS + (16 * w + 4 * g) * 2;
;                     const v2u qw = *(const LAS v2u*)pq, kw = *(const LAS v2u*)(pq + IMG);
;                     const f32x4 dd = ct[t] - cref;
;                     const f32x4 tt = (f32x4){__builtin_amdgcn_fmed3f(dd[0], -80.f, 80.f), __builtin_amdgcn_fmed3f(dd[1], -80.f, 80.f), __builtin_amdgcn_fmed3f(dd[2], -80.f, 80.f), __builtin_amdgcn_fmed3f(dd[3], -80.f, 80.f)} * 1.4426950408889634f;
;                     const f32x4 e1 = {__builtin_amdgcn_exp2f(tt[0]), __builtin_amdgcn_exp2f(tt[1]), __builtin_amdgcn_exp2f(tt[2]), __builtin_amdgcn_exp2f(tt[3])};
	v_lshl_add_u64 v[94:95], v[188:189], 0, v[102:103]
	v_lshl_add_u64 v[98:99], v[196:197], 0, v[102:103]
	v_lshl_add_u64 v[102:103], v[198:199], 0, v[102:103]
	v_lshl_add_u64 v[106:107], v[188:189], 0, v[114:115]
	v_lshlrev_b64 v[118:119], 12, v[118:119]
	global_load_dwordx4 v[102:105], v[102:103], off
	v_lshl_add_u64 v[118:119], v[216:217], 0, v[118:119]
	global_load_dwordx4 v[110:113], v[106:107], off
	v_lshl_add_u64 v[106:107], v[196:197], 0, v[114:115]
	v_lshl_add_u64 v[114:115], v[198:199], 0, v[114:115]
	global_load_dwordx4 v[94:97], v[94:95], off
	v_mov_b32_e32 v126, 0x3f803f80
	global_load_dwordx4 v[98:101], v[98:99], off
	s_or_b64 s[34:35], s[4:5], s[26:27]
	global_load_dwordx4 v[106:109], v[106:107], off
	s_and_b64 vcc, exec, s[34:35]
	global_load_dwordx4 v[114:117], v[114:115], off
	s_nop 0
	global_load_dwordx4 v[118:121], v[118:119], off
	ds_read_b64_tr_b16 v[122:123], v245 offset:36864
	ds_read_b64_tr_b16 v[124:125], v245 offset:38016
	ds_read_b64_tr_b16 v[138:139], v245 offset:46080
	ds_read_b64_tr_b16 v[140:141], v245 offset:47232
	v_mov_b32_e32 v127, v126
	v_mov_b32_e32 v128, v126
	v_mov_b32_e32 v129, v126
	s_waitcnt lgkmcnt(2)
	v_mfma_f32_16x16x32_bf16 v[142:145], v[122:125], v[10:13], v[2:5]
	v_mfma_f32_16x16x32_bf16 v[146:149], v[122:125], v[6:9], v[2:5]
	v_mfma_f32_16x16x32_bf16 v[122:125], v[122:125], v[126:129], v[2:5]
	s_waitcnt lgkmcnt(0)
	v_mfma_f32_16x16x32_bf16 v[134:137], v[138:141], v[10:13], v[122:125]
	v_mfma_f32_16x16x32_bf16 v[130:133], v[138:141], v[6:9], v[122:125]
	s_nop 4
	v_sub_f32_e32 v145, v145, v125
	v_sub_f32_e32 v144, v144, v124
	v_sub_f32_e32 v143, v143, v123
	v_mfma_f32_16x16x32_bf16 v[126:129], v[138:141], v[126:129], v[122:125]
	v_mul_f32_e32 v138, 0x3fb8aa3b, v122
	v_mul_f32_e32 v139, 0x3fb8aa3b, v123
	v_mul_f32_e32 v140, 0x3fb8aa3b, v124
	v_mul_f32_e32 v141, 0x3fb8aa3b, v125
	v_exp_f32_e32 v138, v138
	v_exp_f32_e32 v139, v139
	v_exp_f32_e32 v140, v140
	v_exp_f32_e32 v141, v141
	v_sub_f32_e32 v142, v142, v122
	v_pk_mul_f32 v[152:153], v[214:215], v[138:139]
	v_med3_f32 v142, v142, s95, v182
	v_pk_mul_f32 v[150:151], v[218:219], v[140:141]
	v_cvt_pk_bf16_f32 v152, v152, v153
	v_cvt_pk_bf16_f32 v153, v150, v151
	ds_write_b64 v246, v[152:153]
	v_pk_mul_f32 v[150:151], v[212:213], v[140:141]
	v_pk_mul_f32 v[152:153], v[210:211], v[138:139]
	v_med3_f32 v143, v143, s95, v182
	v_cvt_pk_bf16_f32 v152, v152, v153
	v_cvt_pk_bf16_f32 v153, v150, v151
	v_med3_f32 v144, v144, s95, v182
	v_med3_f32 v145, v145, s95, v182
	ds_write_b64 v246, v[152:153] offset:4608
	v_pk_mul_f32 v[150:151], v[208:209], v[140:141]
	v_pk_mul_f32 v[152:153], v[206:207], v[138:139]
	v_pk_mul_f32 v[140:141], v[204:205], v[140:141]
	v_pk_mul_f32 v[138:139], v[202:203], v[138:139]
	v_pk_mul_f32 v[144:145], v[144:145], s[56:57] op_sel_hi:[1,0]
	v_pk_mul_f32 v[142:143], v[142:143], s[56:57] op_sel_hi:[1,0]
	v_cvt_pk_bf16_f32 v152, v152, v153
	v_cvt_pk_bf16_f32 v153, v150, v151
	v_cvt_pk_bf16_f32 v138, v138, v139
	v_cvt_pk_bf16_f32 v139, v140, v141
	v_exp_f32_e32 v142, v142
	v_exp_f32_e32 v143, v143
	v_exp_f32_e32 v144, v144
	v_exp_f32_e32 v145, v145
	ds_write_b64 v246, v[152:153] offset:9216
	ds_write_b64 v246, v[138:139] offset:13824
	ds_read_b64 v[138:139], v247
	ds_read_b64 v[140:141], v247 offset:18432
	v_rcp_f32_e32 v150, v142
	v_rcp_f32_e32 v151, v143
	v_rcp_f32_e32 v152, v144
	v_rcp_f32_e32 v153, v145
	s_waitcnt lgkmcnt(1)
	v_lshlrev_b32_e32 v154, 16, v138
	v_and_b32_e32 v155, 0xffff0000, v138
	v_lshlrev_b32_e32 v138, 16, v139
	v_and_b32_e32 v139, 0xffff0000, v139
	v_pk_mul_f32 v[138:139], v[144:145], v[138:139]
	v_pk_mul_f32 v[142:143], v[142:143], v[154:155]
	s_waitcnt lgkmcnt(0)
	v_lshlrev_b32_e32 v144, 16, v140
	v_and_b32_e32 v145, 0xffff0000, v140
	v_lshlrev_b32_e32 v140, 16, v141
	v_and_b32_e32 v141, 0xffff0000, v141
	v_pk_mul_f32 v[140:141], v[152:153], v[140:141]
	v_pk_mul_f32 v[144:145], v[150:151], v[144:145]
	v_cvt_pk_bf16_f32 v142, v142, v143
	v_cvt_pk_bf16_f32 v143, v138, v139
	v_cvt_pk_bf16_f32 v138, v144, v145
	v_cvt_pk_bf16_f32 v139, v140, v141
	ds_write_b64 v247, v[142:143]
	ds_write_b64 v247, v[138:139] offset:18432
	v_sub_f32_e32 v145, v149, v125
	v_sub_f32_e32 v144, v148, v124
	v_sub_f32_e32 v143, v147, v123
	v_sub_f32_e32 v142, v146, v122
	v_med3_f32 v142, v142, s95, v182
	v_med3_f32 v143, v143, s95, v182
	v_med3_f32 v144, v144, s95, v182
	v_med3_f32 v145, v145, s95, v182
	v_pk_mul_f32 v[144:145], v[144:145], s[56:57] op_sel_hi:[1,0]
	v_pk_mul_f32 v[142:143], v[142:143], s[56:57] op_sel_hi:[1,0]
	v_exp_f32_e32 v144, v144
	v_exp_f32_e32 v142, v142
	v_exp_f32_e32 v143, v143
	v_exp_f32_e32 v145, v145
	ds_read_b64 v[138:139], v247 offset:4608
	ds_read_b64 v[140:141], v247 offset:23040
	v_rcp_f32_e32 v146, v142
	v_rcp_f32_e32 v147, v143
	v_rcp_f32_e32 v148, v144
	v_rcp_f32_e32 v149, v145
	v_sub_f32_e32 v137, v137, v125
	v_sub_f32_e32 v136, v136, v124
	v_sub_f32_e32 v135, v135, v123
	v_sub_f32_e32 v134, v134, v122
	s_waitcnt lgkmcnt(1)
	v_lshlrev_b32_e32 v150, 16, v138
	v_and_b32_e32 v151, 0xffff0000, v138
	v_lshlrev_b32_e32 v138, 16, v139
	v_and_b32_e32 v139, 0xffff0000, v139
	v_med3_f32 v134, v134, s95, v182
	v_med3_f32 v135, v135, s95, v182
	v_med3_f32 v136, v136, s95, v182
	v_med3_f32 v137, v137, s95, v182
	v_pk_mul_f32 v[138:139], v[144:145], v[138:139]
	v_pk_mul_f32 v[142:143], v[142:143], v[150:151]
	s_waitcnt lgkmcnt(0)
; __device__ __forceinline__ void mixer_hg2(const Args& a, Frame& F, bool ctx_out) {
;     ...
;                 for (int t = 0; t < 4; ++t) {
;                     LAS unsigned char* pq = L + (16 * t + i) * QS + (16 * w + 4 * g) * 2;
;                     const v2u qw = *(const LAS v2u*)pq, kw = *(const LAS v2u*)(pq + IMG);
;                     const f32x4 dd = ct[t] - cref;
;                     const f32x4 tt = (f32x4){__builtin_amdgcn_fmed3f(dd[0], -80.f, 80.f), __builtin_amdgcn_fmed3f(dd[1], -80.f, 80.f), __builtin_amdgcn_fmed3f(dd[2], -80.f, 80.f), __builtin_amdgcn_fmed3f(dd[3], -80.f, 80.f)} * 1.4426950408889634f;
;                     const f32x4 e1 = {__builtin_amdgcn_exp2f(tt[0]), __builtin_amdgcn_exp2f(tt[1]), __builtin_amdgcn_exp2f(tt[2]), __builtin_amdgcn_exp2f(tt[3])};
;                     const f32x4 e2 = {__builtin_amdgcn_rcpf(e1[0]), __builtin_amdgcn_rcpf(e1[1]), __builtin_amdgcn_rcpf(e1[2]), __builtin_amdgcn_rcpf(e1[3])};
;                     const f32x4 q4 = (f32x4){bflo(qw.x), bfhi(qw.x), bflo(qw.y), bfhi(qw.y)} * e1, k4 = (f32x4){bflo(kw.x), bfhi(kw.x), bflo(kw.y), bfhi(kw.y)} * e2;
;                     v2u qo, ko;
;                     qo.x = pk2(q4[0], q4[1]); qo.y = pk2(q4[2], q4[3]);
;                     ko.x = pk2(k4[0], k4[1]); ko.y = pk2(k4[2], k4[3]);
;                     *(LAS v2u*)pq = qo; *(LAS v2u*)(pq + IMG) = ko;
;                 }
;             }
;             MX_BAR();
;             const int rlo = H2_ROWLO(c);
;             const bool do_out = ctx_out || c >= NCTX;
;             mx_bf16x8 aq[KS];
;             {
;                 mx_bf16x8 kf[2][KS], vt[4][2];
;                 if (do_out) {
; #pragma unroll
;                     for (int ks = 0; ks < KS; ++ks) { aq[ks] = frag_row(L, QS, nq0, 32 * ks, lane); kf[0][ks] = frag_row(L + IMG, QS, 32 * cg, 32 * ks, lane); kf[1][ks] = frag_row(L + IMG, QS, 32 * cg + 16, 32 * ks, lane); }
;                 }
; #pragma unroll
;                 for (int te = 0; te < 4; ++te) { vt[te][0] = frag_row8(L + O_VT, 16 * te, 0, lane); vt[te][1] = frag_row8(L + O_VT, 16 * te, 32, lane); }
;                 const mx_bf16x8 ak0 = frag_tr(L + IMG, QS, 0, 16 * w, lane), ak1 = frag_tr(L + IMG, QS, 32, 16 * w, lane);
;                 __builtin_amdgcn_sched_barrier(0);
;                 f32x4 pt0 = ZERO4, pt1 = ZERO4;
;                 if (do_out) {
; #pragma unroll
	v_lshlrev_b32_e32 v144, 16, v140
	v_and_b32_e32 v145, 0xffff0000, v140
	v_lshlrev_b32_e32 v140, 16, v141
	v_and_b32_e32 v141, 0xffff0000, v141
	v_pk_mul_f32 v[136:137], v[136:137], s[56:57] op_sel_hi:[1,0]
	v_pk_mul_f32 v[134:135], v[134:135], s[56:57] op_sel_hi:[1,0]
	v_pk_mul_f32 v[140:141], v[148:149], v[140:141]
	v_pk_mul_f32 v[144:145], v[146:147], v[144:145]
	v_cvt_pk_bf16_f32 v142, v142, v143
	v_cvt_pk_bf16_f32 v143, v138, v139
	v_exp_f32_e32 v134, v134
	v_exp_f32_e32 v135, v135
	v_exp_f32_e32 v136, v136
	v_exp_f32_e32 v137, v137
	v_cvt_pk_bf16_f32 v138, v144, v145
	v_cvt_pk_bf16_f32 v139, v140, v141
	ds_write_b64 v247, v[142:143] offset:4608
	ds_write_b64 v247, v[138:139] offset:23040
	ds_read_b64 v[138:139], v247 offset:9216
	ds_read_b64 v[140:141], v247 offset:27648
	v_rcp_f32_e32 v142, v134
	v_rcp_f32_e32 v143, v135
	v_rcp_f32_e32 v144, v136
	v_rcp_f32_e32 v145, v137
	v_sub_f32_e32 v133, v133, v125
	v_sub_f32_e32 v132, v132, v124
	v_sub_f32_e32 v131, v131, v123
	v_sub_f32_e32 v130, v130, v122
	s_waitcnt lgkmcnt(1)
	v_lshlrev_b32_e32 v146, 16, v138
	v_and_b32_e32 v147, 0xffff0000, v138
	v_lshlrev_b32_e32 v138, 16, v139
	v_and_b32_e32 v139, 0xffff0000, v139
	v_med3_f32 v130, v130, s95, v182
	v_med3_f32 v131, v131, s95, v182
	v_med3_f32 v132, v132, s95, v182
	v_med3_f32 v133, v133, s95, v182
	v_pk_mul_f32 v[136:137], v[136:137], v[138:139]
	v_pk_mul_f32 v[134:135], v[134:135], v[146:147]
	s_waitcnt lgkmcnt(0)
	v_lshlrev_b32_e32 v138, 16, v140
	v_and_b32_e32 v139, 0xffff0000, v140
	v_lshlrev_b32_e32 v140, 16, v141
	v_and_b32_e32 v141, 0xffff0000, v141
	v_pk_mul_f32 v[132:133], v[132:133], s[56:57] op_sel_hi:[1,0]
	v_pk_mul_f32 v[130:131], v[130:131], s[56:57] op_sel_hi:[1,0]
	v_pk_mul_f32 v[140:141], v[144:145], v[140:141]
	v_pk_mul_f32 v[138:139], v[142:143], v[138:139]
	v_cvt_pk_bf16_f32 v134, v134, v135
	v_cvt_pk_bf16_f32 v135, v136, v137
	v_exp_f32_e32 v130, v130
	v_exp_f32_e32 v131, v131
	v_exp_f32_e32 v132, v132
	v_exp_f32_e32 v133, v133
	v_cvt_pk_bf16_f32 v136, v138, v139
	v_cvt_pk_bf16_f32 v137, v140, v141
	ds_write_b64 v247, v[134:135] offset:9216
	ds_write_b64 v247, v[136:137] offset:27648
	ds_read_b64 v[134:135], v247 offset:13824
	ds_read_b64 v[136:137], v247 offset:32256
	v_rcp_f32_e32 v138, v130
	v_rcp_f32_e32 v139, v131
	v_rcp_f32_e32 v140, v132
	v_rcp_f32_e32 v141, v133
	s_waitcnt lgkmcnt(1)
	v_lshlrev_b32_e32 v142, 16, v134
	v_and_b32_e32 v143, 0xffff0000, v134
	v_lshlrev_b32_e32 v134, 16, v135
	v_and_b32_e32 v135, 0xffff0000, v135
	v_pk_mul_f32 v[132:133], v[132:133], v[134:135]
	v_pk_mul_f32 v[130:131], v[130:131], v[142:143]
	s_waitcnt lgkmcnt(0)
	v_lshlrev_b32_e32 v134, 16, v136
	v_and_b32_e32 v135, 0xffff0000, v136
	v_lshlrev_b32_e32 v136, 16, v137
	v_and_b32_e32 v137, 0xffff0000, v137
	v_pk_mul_f32 v[136:137], v[140:141], v[136:137]
	v_pk_mul_f32 v[134:135], v[138:139], v[134:135]
	v_cvt_pk_bf16_f32 v130, v130, v131
	v_cvt_pk_bf16_f32 v131, v132, v133
	v_cvt_pk_bf16_f32 v132, v134, v135
	v_cvt_pk_bf16_f32 v133, v136, v137
	ds_write_b64 v247, v[130:131] offset:13824
	ds_write_b64 v247, v[132:133] offset:32256
	s_waitcnt lgkmcnt(0)
	s_barrier
	s_cbranch_vccz .LBB0_514
	v_add_u32_e32 v42, v230, v232
	v_add_u32_e32 v54, v231, v232
	ds_read_b128 v[14:17], v42
	ds_read_b128 v[18:21], v42 offset:64
	ds_read_b128 v[30:33], v54 offset:18432
	ds_read_b128 v[38:41], v54 offset:18496
	ds_read_b128 v[26:29], v54 offset:23040
	ds_read_b128 v[34:37], v54 offset:23104
	ds_read_b128 v[22:25], v42 offset:128
	ds_read_b128 v[42:45], v42 offset:192
	ds_read_b128 v[50:53], v54 offset:18560
	ds_read_b128 v[58:61], v54 offset:18624
	ds_read_b128 v[46:49], v54 offset:23168
	ds_read_b128 v[54:57], v54 offset:23232
.LBB0_514:
	ds_read_b128 v[138:141], v244 offset:55296
	ds_read_b128 v[130:133], v244 offset:55360
	ds_read_b128 v[142:145], v244 offset:57600
	ds_read_b128 v[134:137], v244 offset:57664
	ds_read_b128 v[158:161], v244 offset:59904
	ds_read_b128 v[146:149], v244 offset:59968
	ds_read_b128 v[162:165], v244 offset:62208
	ds_read_b128 v[150:153], v244 offset:62272
	ds_read_b64_tr_b16 v[170:171], v245 offset:18432
	ds_read_b64_tr_b16 v[172:173], v245 offset:19584
	ds_read_b64_tr_b16 v[166:167], v245 offset:27648
	ds_read_b64_tr_b16 v[168:169], v245 offset:28800
	v_cndmask_b32_e64 v154, 0, 1, s[34:35]
	v_cmp_ne_u32_e64 s[26:27], 1, v154
	s_andn2_b64 vcc, exec, s[34:35]
	v_mov_b32_e32 v174, v2
	v_mov_b32_e32 v175, v2
	v_mov_b32_e32 v176, v2
	v_mov_b32_e32 v177, v2
	v_mov_b32_e32 v154, v2
	v_mov_b32_e32 v155, v2
	v_mov_b32_e32 v156, v2
	v_mov_b32_e32 v157, v2
	s_cbranch_vccnz .LBB0_516
	s_waitcnt lgkmcnt(14)
	v_mfma_f32_16x16x32_bf16 v[154:157], v[30:33], v[14:17], v[2:5]
	v_mfma_f32_16x16x32_bf16 v[174:177], v[26:29], v[14:17], v[2:5]
	v_mfma_f32_16x16x32_bf16 v[154:157], v[38:41], v[18:21], v[154:157]
	v_mfma_f32_16x16x32_bf16 v[174:177], v[34:37], v[18:21], v[174:177]
	v_mfma_f32_16x16x32_bf16 v[154:157], v[50:53], v[22:25], v[154:157]
	s_waitcnt lgkmcnt(13)
	v_mfma_f32_16x16x32_bf16 v[178:181], v[46:49], v[22:25], v[174:177]
	v_mfma_f32_16x16x32_bf16 v[174:177], v[58:61], v[42:45], v[154:157]
	s_waitcnt lgkmcnt(12)
	v_mfma_f32_16x16x32_bf16 v[154:157], v[54:57], v[42:45], v[178:181]
; #define LAS __attribute__((address_space(3)))
; __device__ __forceinline__ void mixer_hg2(const Args& a, Frame& F, bool ctx_out) {
;     ...
;                 if (do_out) {
; #pragma unroll
;                     for (int ks = 0; ks < KS; ++ks) { pt0 = MX_MFMA(kf[0][ks], aq[ks], pt0); pt1 = MX_MFMA(kf[1][ks], aq[ks], pt1); }
;                 }
;                 f32x4 uu[4];
; #pragma unroll
;                 for (int te = 0; te < 4; ++te) { const f32x4 z4 = ZERO4; uu[te] = MX_MFMA(ak0, vt[te][0], z4); }
; #pragma unroll
;                 for (int te = 0; te < 4; ++te) uu[te] = MX_MFMA(ak1, vt[te][1], uu[te]);
;                 __builtin_amdgcn_sched_barrier(0);
;                 if (do_out) {
;                     const int m0 = 32 * cg + 4 * g, m1 = m0 + 16, n = nq0 + i;
;                     v2u pw; pw.x = pk2((m0 <= n) ? pt0[0] : 0.f, (m0 + 1 <= n) ? pt0[1] : 0.f); pw.y = pk2((m0 + 2 <= n) ? pt0[2] : 0.f, (m0 + 3 <= n) ? pt0[3] : 0.f);
;                     *(LAS v2u*)(L + O_P + n * PS + m0 * 2) = pw;
;                     pw.x = pk2((m1 <= n) ? pt1[0] : 0.f, (m1 + 1 <= n) ? pt1[1] : 0.f); pw.y = pk2((m1 + 2 <= n) ? pt1[2] : 0.f, (m1 + 3 <= n) ? pt1[3] : 0.f);
;                     *(LAS v2u*)(L + O_P + n * PS + m1 * 2) = pw;
;                 }
; #pragma unroll
;                 for (int te = 0; te < 4; ++te) accS[te] = accS[te] * fe + uu[te] * fu;
;             }
;             mx_bf16x8 st[2][KS], vo[2][2];
;             if (do_out) {
; #pragma unroll
;                 for (int te = 0; te < 2; ++te)
; #pragma unroll
;                     for (int ks = 0; ks < KS; ++ks) st[te][ks] = frag_row(L + O_ST, QS, 32 * cg + 16 * te, 32 * ks, lane);
;             }
;             MX_BAR();
;             if (do_out) {
;                 const mx_bf16x8 bp0 = frag_row8(L + O_P, nq0, 0, lane), bp1 = frag_row8(L + O_P, nq0, 32, lane);
; #pragma unroll
;                 for (int te = 0; te < 2; ++te) { vo[te][0] = frag_row8(L + O_VT, 32 * cg + 16 * te, 0, lane); vo[te][1] = frag_row8(L + O_VT, 32 * cg + 16 * te, 32, lane); }
;                 __builtin_amdgcn_sched_barrier(0);
;                 f32x4 oa = ZERO4, ob = oa;
;                 oa = MX_MFMA(vo[0][0], bp0, oa); ob = MX_MFMA(vo[1][0], bp0, ob);
; #pragma unroll
;                 for (int ks = 0; ks < KS; ++ks) { oa = MX_MFMA(st[0][ks], aq[ks], oa); ob = MX_MFMA(st[1][ks], aq[ks], ob); }
.LBB0_516:
	s_waitcnt lgkmcnt(2)
	v_mfma_f32_16x16x32_bf16 v[138:141], v[170:173], v[138:141], v[2:5]
	v_mfma_f32_16x16x32_bf16 v[178:181], v[170:173], v[142:145], v[2:5]
	v_mfma_f32_16x16x32_bf16 v[158:161], v[170:173], v[158:161], v[2:5]
	v_mfma_f32_16x16x32_bf16 v[162:165], v[170:173], v[162:165], v[2:5]
	s_waitcnt lgkmcnt(0)
	v_mfma_f32_16x16x32_bf16 v[142:145], v[166:169], v[130:133], v[138:141]
	v_mfma_f32_16x16x32_bf16 v[138:141], v[166:169], v[134:137], v[178:181]
	v_mfma_f32_16x16x32_bf16 v[134:137], v[166:169], v[146:149], v[158:161]
	v_mfma_f32_16x16x32_bf16 v[130:133], v[166:169], v[150:153], v[162:165]
	s_and_b64 vcc, exec, s[26:27]
	s_cbranch_vccnz .LBB0_518
	v_cndmask_b32_e64 v146, v174, 0, s[8:9]
	v_cndmask_b32_e64 v147, 0, v175, s[10:11]
	v_cvt_pk_bf16_f32 v146, v146, v147
	v_cndmask_b32_e64 v147, v176, 0, s[12:13]
	v_cndmask_b32_e64 v148, v177, 0, s[14:15]
	v_cvt_pk_bf16_f32 v147, v147, v148
	v_add_u32_e32 v148, v233, v234
	ds_write_b64 v148, v[146:147] offset:64512
	v_cndmask_b32_e64 v146, v154, 0, s[16:17]
	v_cndmask_b32_e64 v147, v155, 0, s[18:19]
	v_cvt_pk_bf16_f32 v146, v146, v147
	v_cndmask_b32_e64 v147, v156, 0, s[20:21]
	v_cndmask_b32_e64 v148, v157, 0, s[22:23]
	v_cvt_pk_bf16_f32 v147, v147, v148
	v_add_u32_e32 v148, v233, v235
	ds_write_b64 v148, v[146:147] offset:64512
.LBB0_518:
	s_and_b64 vcc, exec, s[26:27]
	s_cbranch_vccnz .LBB0_520
	v_add_u32_e32 v90, v242, v232
	ds_read_b128 v[62:65], v90
	ds_read_b128 v[66:69], v90 offset:64
	ds_read_b128 v[70:73], v90 offset:128
	ds_read_b128 v[74:77], v90 offset:192
	ds_read_b128 v[78:81], v90 offset:4608
	ds_read_b128 v[82:85], v90 offset:4672
	ds_read_b128 v[86:89], v90 offset:4736
	ds_read_b128 v[90:93], v90 offset:4800
.LBB0_520:
	s_waitcnt lgkmcnt(0)
	s_barrier
	s_and_b64 vcc, exec, s[26:27]
	s_cbranch_vccnz .LBB0_522
	v_sub_co_u32_e64 v146, s[26:27], s31, 4
	s_and_b64 s[34:35], s[24:25], exec
	v_readfirstlane_b32 s34, v146
	v_add_u32_e32 v150, v233, v232
	v_add_u32_e32 v166, v243, v232
	s_cselect_b32 s34, s34, s30
	ds_read_b128 v[146:149], v150 offset:64512
	ds_read_b128 v[150:153], v150 offset:64576
	ds_read_b128 v[154:157], v166 offset:55296
	ds_read_b128 v[158:161], v166 offset:55360
	ds_read_b128 v[162:165], v166 offset:57600
	ds_read_b128 v[166:169], v166 offset:57664
	s_lshl_b32 s37, s34, 6
	s_sub_i32 s30, s30, 64
	s_and_b64 s[34:35], s[24:25], exec
	s_cselect_b32 s30, s31, s30
	s_lshl_b32 s30, s30, 6
	s_add_i32 s30, s30, s33
	s_add_i32 s37, s37, s7
	s_and_b64 s[26:27], s[26:27], exec
	s_cselect_b32 s26, s30, s37
	s_waitcnt lgkmcnt(3)
	v_mfma_f32_16x16x32_bf16 v[154:157], v[154:157], v[146:149], v[2:5]
	s_waitcnt lgkmcnt(1)
	v_mfma_f32_16x16x32_bf16 v[146:149], v[162:165], v[146:149], v[2:5]
	v_add_u32_e32 v162, s26, v248
	v_ashrrev_i32_e32 v163, 31, v162
	v_lshlrev_b64 v[162:163], 12, v[162:163]
	v_mfma_f32_16x16x32_bf16 v[154:157], v[62:65], v[14:17], v[154:157]
	v_mfma_f32_16x16x32_bf16 v[146:149], v[78:81], v[14:17], v[146:149]
	v_mfma_f32_16x16x32_bf16 v[154:157], v[66:69], v[18:21], v[154:157]
	v_mfma_f32_16x16x32_bf16 v[146:149], v[82:85], v[18:21], v[146:149]
	v_mfma_f32_16x16x32_bf16 v[154:157], v[70:73], v[22:25], v[154:157]
	v_mfma_f32_16x16x32_bf16 v[146:149], v[86:89], v[22:25], v[146:149]
	v_mfma_f32_16x16x32_bf16 v[154:157], v[74:77], v[42:45], v[154:157]
	v_mfma_f32_16x16x32_bf16 v[146:149], v[90:93], v[42:45], v[146:149]
	v_mfma_f32_16x16x32_bf16 v[154:157], v[158:161], v[150:153], v[154:157]
	v_lshl_add_u64 v[158:159], v[194:195], 0, v[162:163]
	s_waitcnt lgkmcnt(0)
	v_mfma_f32_16x16x32_bf16 v[146:149], v[166:169], v[150:153], v[146:149]
	s_nop 4
	v_cvt_pk_bf16_f32 v154, v154, v155
	v_cvt_pk_bf16_f32 v155, v156, v157
	s_nop 0
	v_cvt_pk_bf16_f32 v146, v146, v147
	v_cvt_pk_bf16_f32 v147, v148, v149
	global_store_dwordx2 v[158:159], v[154:155], off
	global_store_dwordx2 v[158:159], v[146:147], off offset:32
